# gMLP gate units (L=128): the 4-iteration load->wait->ds_write_b16 staging loop of the v_n tile unrolled to 4 loads in flight with counted waits; stacked on attention fast path + early invalidate + GEM
# baseline (speedup 1.0000x reference)
.LBB0_863:
	v_ashrrev_i32_e32 v8, 4, v5
	v_add_u32_e32 v6, s36, v8
	v_ashrrev_i32_e32 v7, 31, v6
	v_lshlrev_b64 v[6:7], 12, v[6:7]
	v_and_b32_e32 v9, 0x78, v4
	v_lshl_add_u64 v[6:7], s[92:93], 0, v[6:7]
	v_lshlrev_b32_e32 v112, 1, v9
	v_lshl_add_u64 v[6:7], v[6:7], 0, v[112:113]
	v_mul_u32_u24_e32 v9, 0x110, v9
	v_lshlrev_b32_e32 v8, 1, v8
	v_add3_u32 v10, 0, v9, v8
	v_mov_b32_e32 v232, v6
	v_mov_b32_e32 v233, v7
	s_mov_b64 s[98:99], 0x20000
	global_load_dwordx4 v[216:219], v[232:233], off
	v_lshl_add_u64 v[232:233], v[232:233], 0, s[98:99]
	global_load_dwordx4 v[220:223], v[232:233], off
	v_lshl_add_u64 v[232:233], v[232:233], 0, s[98:99]
	global_load_dwordx4 v[224:227], v[232:233], off
	v_lshl_add_u64 v[232:233], v[232:233], 0, s[98:99]
	global_load_dwordx4 v[228:231], v[232:233], off
	s_waitcnt vmcnt(3)
	ds_write_b16 v10, v216 offset:0
	ds_write_b16_d16_hi v10, v216 offset:272
	ds_write_b16 v10, v217 offset:544
	ds_write_b16_d16_hi v10, v217 offset:816
	ds_write_b16 v10, v218 offset:1088
	ds_write_b16_d16_hi v10, v218 offset:1360
	ds_write_b16 v10, v219 offset:1632
	ds_write_b16_d16_hi v10, v219 offset:1904
	s_waitcnt vmcnt(2)
	ds_write_b16 v10, v220 offset:64
	ds_write_b16_d16_hi v10, v220 offset:336
	ds_write_b16 v10, v221 offset:608
	ds_write_b16_d16_hi v10, v221 offset:880
	ds_write_b16 v10, v222 offset:1152
	ds_write_b16_d16_hi v10, v222 offset:1424
	ds_write_b16 v10, v223 offset:1696
	ds_write_b16_d16_hi v10, v223 offset:1968
	s_waitcnt vmcnt(1)
	ds_write_b16 v10, v224 offset:128
	ds_write_b16_d16_hi v10, v224 offset:400
	ds_write_b16 v10, v225 offset:672
	ds_write_b16_d16_hi v10, v225 offset:944
	ds_write_b16 v10, v226 offset:1216
	ds_write_b16_d16_hi v10, v226 offset:1488
	ds_write_b16 v10, v227 offset:1760
	ds_write_b16_d16_hi v10, v227 offset:2032
	s_waitcnt vmcnt(0)
	ds_write_b16 v10, v228 offset:192
	ds_write_b16_d16_hi v10, v228 offset:464
	ds_write_b16 v10, v229 offset:736
	ds_write_b16_d16_hi v10, v229 offset:1008
	ds_write_b16 v10, v230 offset:1280
	ds_write_b16_d16_hi v10, v230 offset:1552
	ds_write_b16 v10, v231 offset:1824
	ds_write_b16_d16_hi v10, v231 offset:2096
	s_movk_i32 s37, 0x5ff
	s_mov_b64 s[94:95], exec

.LBB0_1036:
	v_ashrrev_i32_e32 v8, 4, v5
	v_add_u32_e32 v6, s37, v8
	v_ashrrev_i32_e32 v7, 31, v6
	v_lshlrev_b64 v[6:7], 12, v[6:7]
	v_and_b32_e32 v9, 0x78, v4
	v_lshl_add_u64 v[6:7], s[78:79], 0, v[6:7]
	v_lshlrev_b32_e32 v110, 1, v9
	v_lshl_add_u64 v[6:7], v[6:7], 0, v[110:111]
	v_mul_u32_u24_e32 v9, 0x110, v9
	v_lshlrev_b32_e32 v8, 1, v8
	v_add3_u32 v10, 0, v9, v8
	v_mov_b32_e32 v232, v6
	v_mov_b32_e32 v233, v7
	s_mov_b64 s[98:99], 0x20000
	global_load_dwordx4 v[216:219], v[232:233], off
	v_lshl_add_u64 v[232:233], v[232:233], 0, s[98:99]
	global_load_dwordx4 v[220:223], v[232:233], off
	v_lshl_add_u64 v[232:233], v[232:233], 0, s[98:99]
	global_load_dwordx4 v[224:227], v[232:233], off
	v_lshl_add_u64 v[232:233], v[232:233], 0, s[98:99]
	global_load_dwordx4 v[228:231], v[232:233], off
	s_waitcnt vmcnt(3)
	ds_write_b16 v10, v216 offset:0
	ds_write_b16_d16_hi v10, v216 offset:272
	ds_write_b16 v10, v217 offset:544
	ds_write_b16_d16_hi v10, v217 offset:816
	ds_write_b16 v10, v218 offset:1088
	ds_write_b16_d16_hi v10, v218 offset:1360
	ds_write_b16 v10, v219 offset:1632
	ds_write_b16_d16_hi v10, v219 offset:1904
	s_waitcnt vmcnt(2)
	ds_write_b16 v10, v220 offset:64
	ds_write_b16_d16_hi v10, v220 offset:336
	ds_write_b16 v10, v221 offset:608
	ds_write_b16_d16_hi v10, v221 offset:880
	ds_write_b16 v10, v222 offset:1152
	ds_write_b16_d16_hi v10, v222 offset:1424
	ds_write_b16 v10, v223 offset:1696
	ds_write_b16_d16_hi v10, v223 offset:1968
	s_waitcnt vmcnt(1)
	ds_write_b16 v10, v224 offset:128
	ds_write_b16_d16_hi v10, v224 offset:400
	ds_write_b16 v10, v225 offset:672
	ds_write_b16_d16_hi v10, v225 offset:944
	ds_write_b16 v10, v226 offset:1216
	ds_write_b16_d16_hi v10, v226 offset:1488
	ds_write_b16 v10, v227 offset:1760
	ds_write_b16_d16_hi v10, v227 offset:2032
	s_waitcnt vmcnt(0)
	ds_write_b16 v10, v228 offset:192
	ds_write_b16_d16_hi v10, v228 offset:464
	ds_write_b16 v10, v229 offset:736
	ds_write_b16_d16_hi v10, v229 offset:1008
	ds_write_b16 v10, v230 offset:1280
	ds_write_b16_d16_hi v10, v230 offset:1552
	ds_write_b16 v10, v231 offset:1824
	ds_write_b16_d16_hi v10, v231 offset:2096
	s_movk_i32 s48, 0x5ff
	s_mov_b64 s[80:81], exec
